# v56 + scan step D: bonus*v and *silu(z) stages as v_fma_mix_f32 on the packed f16 operands (16 unpack cvts incl. 8 SDWA removed)
# baseline (speedup 1.0000x reference)
.Lpub_none:
	s_and_saveexec_b64 s[24:25], s[22:23]
	s_cbranch_execz .LBB0_583
	ds_read_b128 v[20:23], v149 offset:56320
	ds_read_b128 v[24:27], v149 offset:56336
	ds_read2st64_b32 v[8:9], v150 offset1:1
	ds_read_b128 v[28:31], v151 offset:9216
	ds_read_b128 v[32:35], v152
	v_add_u32_e32 v87, 0x14800, v106
	ds_read_b128 v[36:39], v87 offset:2304
	ds_read_b128 v[40:43], v87 offset:2320
	ds_read_b128 v[82:85], v87 offset:2560
	ds_read_b128 v[158:161], v87 offset:2576
	s_waitcnt lgkmcnt(8)
	v_add_f32_e32 v11, 0, v20
	s_waitcnt lgkmcnt(6)
	v_add_f32_e32 v8, v8, v9
	v_add_f32_e32 v9, v21, v11
	v_add_f32_e32 v9, v22, v9
	v_add_f32_e32 v9, v23, v9
	v_add_f32_e32 v9, v24, v9
	v_add_f32_e32 v9, v25, v9
	v_add_f32_e32 v9, v26, v9
	v_add_f32_e32 v9, v27, v9
	s_nop 1
	v_add_f32_dpp v9, v9, v9 quad_perm:[1,0,3,2] row_mask:0xf bank_mask:0xf bound_ctrl:1
	s_nop 1
	v_add_f32_dpp v9, v9, v9 quad_perm:[2,3,0,1] row_mask:0xf bank_mask:0xf bound_ctrl:1
	s_nop 1
	v_add_f32_dpp v9, v9, v9 row_half_mirror row_mask:0xf bank_mask:0xf bound_ctrl:1
	v_mul_f32_e32 v86, 0x3c800000, v9
	v_pk_add_f32 v[20:21], v[20:21], v[86:87] op_sel_hi:[1,0] neg_lo:[0,1] neg_hi:[0,1]
	s_nop 0
	v_pk_mul_f32 v[162:163], v[20:21], v[20:21]
	v_pk_add_f32 v[22:23], v[22:23], v[86:87] op_sel_hi:[1,0] neg_lo:[0,1] neg_hi:[0,1]
	s_nop 0
	v_pk_mul_f32 v[168:169], v[22:23], v[22:23]
	v_add_f32_e32 v9, v162, v163
	v_pk_add_f32 v[24:25], v[24:25], v[86:87] op_sel_hi:[1,0] neg_lo:[0,1] neg_hi:[0,1]
	v_add_f32_e32 v9, v168, v9
	v_pk_mul_f32 v[170:171], v[24:25], v[24:25]
	v_add_f32_e32 v9, v169, v9
	v_pk_add_f32 v[26:27], v[26:27], v[86:87] op_sel_hi:[1,0] neg_lo:[0,1] neg_hi:[0,1]
	v_add_f32_e32 v9, v170, v9
	v_pk_mul_f32 v[86:87], v[26:27], v[26:27]
	v_add_f32_e32 v9, v171, v9
	v_add_f32_e32 v9, v86, v9
	v_add_f32_e32 v9, v87, v9
	s_nop 1
	v_add_f32_dpp v9, v9, v9 quad_perm:[1,0,3,2] row_mask:0xf bank_mask:0xf bound_ctrl:1
	s_nop 1
	v_add_f32_dpp v9, v9, v9 quad_perm:[2,3,0,1] row_mask:0xf bank_mask:0xf bound_ctrl:1
	s_nop 1
	v_add_f32_dpp v9, v9, v9 row_half_mirror row_mask:0xf bank_mask:0xf bound_ctrl:1
	v_fmamk_f32 v9, v9, 0x3c800000, v153
	v_rsq_f32_e32 v86, v9
	s_nop 0
	v_pk_mul_f32 v[20:21], v[20:21], v[86:87] op_sel_hi:[1,0]
	v_pk_mul_f32 v[22:23], v[22:23], v[86:87] op_sel_hi:[1,0]
	v_pk_mul_f32 v[24:25], v[24:25], v[86:87] op_sel_hi:[1,0]
	v_pk_mul_f32 v[26:27], v[26:27], v[86:87] op_sel_hi:[1,0]
	s_waitcnt lgkmcnt(1)
	v_pk_fma_f32 v[20:21], v[36:37], v[20:21], v[82:83]
	v_pk_fma_f32 v[22:23], v[38:39], v[22:23], v[84:85]
	s_waitcnt lgkmcnt(0)
	v_pk_fma_f32 v[24:25], v[40:41], v[24:25], v[158:159]
	v_pk_fma_f32 v[26:27], v[42:43], v[26:27], v[160:161]
	v_fma_mix_f32 v20, v8, v28, v20 op_sel_hi:[0,1,0]
	v_fma_mix_f32 v21, v8, v28, v21 op_sel:[0,1,0] op_sel_hi:[0,1,0]
	v_fma_mix_f32 v22, v8, v29, v22 op_sel_hi:[0,1,0]
	v_fma_mix_f32 v23, v8, v29, v23 op_sel:[0,1,0] op_sel_hi:[0,1,0]
	v_fma_mix_f32 v24, v8, v30, v24 op_sel_hi:[0,1,0]
	v_fma_mix_f32 v25, v8, v30, v25 op_sel:[0,1,0] op_sel_hi:[0,1,0]
	v_fma_mix_f32 v26, v8, v31, v26 op_sel_hi:[0,1,0]
	v_fma_mix_f32 v27, v8, v31, v27 op_sel:[0,1,0] op_sel_hi:[0,1,0]
	v_fma_mix_f32 v20, v20, v32, 0 op_sel_hi:[0,1,0]
	v_fma_mix_f32 v21, v21, v32, 0 op_sel:[0,1,0] op_sel_hi:[0,1,0]
	v_fma_mix_f32 v22, v22, v33, 0 op_sel_hi:[0,1,0]
	v_fma_mix_f32 v23, v23, v33, 0 op_sel:[0,1,0] op_sel_hi:[0,1,0]
	v_fma_mix_f32 v24, v24, v34, 0 op_sel_hi:[0,1,0]
	v_fma_mix_f32 v25, v25, v34, 0 op_sel:[0,1,0] op_sel_hi:[0,1,0]
	v_fma_mix_f32 v26, v26, v35, 0 op_sel_hi:[0,1,0]
	v_fma_mix_f32 v27, v27, v35, 0 op_sel:[0,1,0] op_sel_hi:[0,1,0]
	v_cvt_pk_f16_f32 v20, v20, v21
	v_cvt_pk_f16_f32 v21, v22, v23
	v_cvt_pk_f16_f32 v22, v24, v25
	v_cvt_pk_f16_f32 v23, v26, v27
	v_add_u32_e32 v8, s29, v107
	v_ashrrev_i32_e32 v9, 31, v8
	v_lshlrev_b64 v[8:9], 11, v[8:9]
	v_lshl_add_u64 v[8:9], v[60:61], 0, v[8:9]
	global_store_dwordx4 v[8:9], v[20:23], off sc1
	s_nop 1

.Lsz_skip:
	s_barrier
	s_and_saveexec_b64 s[24:25], s[22:23]
	s_cbranch_execz .Lds_e583
	ds_read_b128 v[20:23], v149 offset:56320
	ds_read_b128 v[24:27], v149 offset:56336
	ds_read2st64_b32 v[8:9], v150 offset1:1
	ds_read_b128 v[28:31], v151 offset:9216
	ds_read_b128 v[32:35], v152
	v_add_u32_e32 v87, 0x14800, v106
	ds_read_b128 v[36:39], v87 offset:2304
	ds_read_b128 v[40:43], v87 offset:2320
	ds_read_b128 v[82:85], v87 offset:2560
	ds_read_b128 v[158:161], v87 offset:2576
	s_waitcnt lgkmcnt(8)
	v_add_f32_e32 v11, 0, v20
	s_waitcnt lgkmcnt(6)
	v_add_f32_e32 v8, v8, v9
	v_add_f32_e32 v9, v21, v11
	v_add_f32_e32 v9, v22, v9
	v_add_f32_e32 v9, v23, v9
	v_add_f32_e32 v9, v24, v9
	v_add_f32_e32 v9, v25, v9
	v_add_f32_e32 v9, v26, v9
	v_add_f32_e32 v9, v27, v9
	s_nop 1
	v_add_f32_dpp v9, v9, v9 quad_perm:[1,0,3,2] row_mask:0xf bank_mask:0xf bound_ctrl:1
	s_nop 1
	v_add_f32_dpp v9, v9, v9 quad_perm:[2,3,0,1] row_mask:0xf bank_mask:0xf bound_ctrl:1
	s_nop 1
	v_add_f32_dpp v9, v9, v9 row_half_mirror row_mask:0xf bank_mask:0xf bound_ctrl:1
	v_mul_f32_e32 v86, 0x3c800000, v9
	v_pk_add_f32 v[20:21], v[20:21], v[86:87] op_sel_hi:[1,0] neg_lo:[0,1] neg_hi:[0,1]
	s_nop 0
	v_pk_mul_f32 v[162:163], v[20:21], v[20:21]
	v_pk_add_f32 v[22:23], v[22:23], v[86:87] op_sel_hi:[1,0] neg_lo:[0,1] neg_hi:[0,1]
	s_nop 0
	v_pk_mul_f32 v[168:169], v[22:23], v[22:23]
	v_add_f32_e32 v9, v162, v163
	v_pk_add_f32 v[24:25], v[24:25], v[86:87] op_sel_hi:[1,0] neg_lo:[0,1] neg_hi:[0,1]
	v_add_f32_e32 v9, v168, v9
	v_pk_mul_f32 v[170:171], v[24:25], v[24:25]
	v_add_f32_e32 v9, v169, v9
	v_pk_add_f32 v[26:27], v[26:27], v[86:87] op_sel_hi:[1,0] neg_lo:[0,1] neg_hi:[0,1]
	v_add_f32_e32 v9, v170, v9
	v_pk_mul_f32 v[86:87], v[26:27], v[26:27]
	v_add_f32_e32 v9, v171, v9
	v_add_f32_e32 v9, v86, v9
	v_add_f32_e32 v9, v87, v9
	s_nop 1
	v_add_f32_dpp v9, v9, v9 quad_perm:[1,0,3,2] row_mask:0xf bank_mask:0xf bound_ctrl:1
	s_nop 1
	v_add_f32_dpp v9, v9, v9 quad_perm:[2,3,0,1] row_mask:0xf bank_mask:0xf bound_ctrl:1
	s_nop 1
	v_add_f32_dpp v9, v9, v9 row_half_mirror row_mask:0xf bank_mask:0xf bound_ctrl:1
	v_fmamk_f32 v9, v9, 0x3c800000, v153
	v_rsq_f32_e32 v86, v9
	s_nop 0
	v_pk_mul_f32 v[20:21], v[20:21], v[86:87] op_sel_hi:[1,0]
	v_pk_mul_f32 v[22:23], v[22:23], v[86:87] op_sel_hi:[1,0]
	v_pk_mul_f32 v[24:25], v[24:25], v[86:87] op_sel_hi:[1,0]
	v_pk_mul_f32 v[26:27], v[26:27], v[86:87] op_sel_hi:[1,0]
	s_waitcnt lgkmcnt(1)
	v_pk_fma_f32 v[20:21], v[36:37], v[20:21], v[82:83]
	v_pk_fma_f32 v[22:23], v[38:39], v[22:23], v[84:85]
	s_waitcnt lgkmcnt(0)
	v_pk_fma_f32 v[24:25], v[40:41], v[24:25], v[158:159]
	v_pk_fma_f32 v[26:27], v[42:43], v[26:27], v[160:161]
	v_fma_mix_f32 v20, v8, v28, v20 op_sel_hi:[0,1,0]
	v_fma_mix_f32 v21, v8, v28, v21 op_sel:[0,1,0] op_sel_hi:[0,1,0]
	v_fma_mix_f32 v22, v8, v29, v22 op_sel_hi:[0,1,0]
	v_fma_mix_f32 v23, v8, v29, v23 op_sel:[0,1,0] op_sel_hi:[0,1,0]
	v_fma_mix_f32 v24, v8, v30, v24 op_sel_hi:[0,1,0]
	v_fma_mix_f32 v25, v8, v30, v25 op_sel:[0,1,0] op_sel_hi:[0,1,0]
	v_fma_mix_f32 v26, v8, v31, v26 op_sel_hi:[0,1,0]
	v_fma_mix_f32 v27, v8, v31, v27 op_sel:[0,1,0] op_sel_hi:[0,1,0]
	v_fma_mix_f32 v20, v20, v32, 0 op_sel_hi:[0,1,0]
	v_fma_mix_f32 v21, v21, v32, 0 op_sel:[0,1,0] op_sel_hi:[0,1,0]
	v_fma_mix_f32 v22, v22, v33, 0 op_sel_hi:[0,1,0]
	v_fma_mix_f32 v23, v23, v33, 0 op_sel:[0,1,0] op_sel_hi:[0,1,0]
	v_fma_mix_f32 v24, v24, v34, 0 op_sel_hi:[0,1,0]
	v_fma_mix_f32 v25, v25, v34, 0 op_sel:[0,1,0] op_sel_hi:[0,1,0]
	v_fma_mix_f32 v26, v26, v35, 0 op_sel_hi:[0,1,0]
	v_fma_mix_f32 v27, v27, v35, 0 op_sel:[0,1,0] op_sel_hi:[0,1,0]
	v_cvt_pk_f16_f32 v20, v20, v21
	v_cvt_pk_f16_f32 v21, v22, v23
	v_cvt_pk_f16_f32 v22, v24, v25
	v_cvt_pk_f16_f32 v23, v26, v27
	v_add_u32_e32 v8, s29, v107
	v_ashrrev_i32_e32 v9, 31, v8
	v_lshlrev_b64 v[8:9], 11, v[8:9]
	v_lshl_add_u64 v[8:9], v[60:61], 0, v[8:9]
	global_store_dwordx4 v[8:9], v[20:23], off sc1
	s_nop 1
